# K-loop: mid-segment s_setprio 0/1 pair (artifact of two back-to-back MMA groups) removed
# baseline (speedup 1.0000x reference)
.LBB0_246:
	s_add_i32 s90, s42, 2
	s_add_u32 s91, s6, 0x80
	s_addc_u32 s43, s7, 0
	s_cmp_eq_u32 s72, s42
	s_cselect_b32 s43, s89, s43
	s_cselect_b32 s42, s88, s91
	s_cselect_b32 s93, s1, s66
	s_cselect_b32 s92, s0, s8
	ds_read_b128 v[128:131], v222
	ds_read_b128 v[132:135], v222 offset:1024
	ds_read_b128 v[136:139], v222 offset:2048
	ds_read_b128 v[140:143], v222 offset:3072
	ds_read_b128 v[168:171], v222 offset:16384
	ds_read_b128 v[172:175], v222 offset:17408
	ds_read_b128 v[176:179], v222 offset:18432
	ds_read_b128 v[180:183], v222 offset:19456
	s_add_i32 m0, s68, 0xc000
	ds_read_b128 v[190:193], v188
	ds_read_b128 v[194:197], v188 offset:1024
	ds_read_b128 v[198:201], v188 offset:2048
	ds_read_b128 v[202:205], v188 offset:3072
	ds_read_b128 v[206:209], v188 offset:4096
	ds_read_b128 v[210:213], v188 offset:5120
	ds_read_b128 v[214:217], v188 offset:6144
	ds_read_b128 v[218:221], v188 offset:7168
	global_load_lds_dwordx4 v162, s[6:7]
	s_add_i32 m0, s68, 0xe000
	s_nop 0
	global_load_lds_dwordx4 v164, s[6:7]
	s_waitcnt vmcnt(8)
	s_waitcnt lgkmcnt(0)
	s_barrier
	s_setprio 1
	s_waitcnt lgkmcnt(0)
	v_mfma_f32_16x16x32_bf16 v[124:127], v[128:131], v[190:193], v[124:127]
	v_mfma_f32_16x16x32_bf16 v[120:123], v[136:139], v[190:193], v[120:123]
	v_mfma_f32_16x16x32_bf16 v[116:119], v[128:131], v[198:201], v[116:119]
	v_mfma_f32_16x16x32_bf16 v[112:115], v[136:139], v[198:201], v[112:115]
	v_mfma_f32_16x16x32_bf16 v[100:103], v[128:131], v[206:209], v[100:103]
	v_mfma_f32_16x16x32_bf16 v[96:99], v[136:139], v[206:209], v[96:99]
	v_mfma_f32_16x16x32_bf16 v[84:87], v[128:131], v[214:217], v[84:87]
	v_mfma_f32_16x16x32_bf16 v[80:83], v[136:139], v[214:217], v[80:83]
	v_mfma_f32_16x16x32_bf16 v[124:127], v[132:135], v[194:197], v[124:127]
	v_mfma_f32_16x16x32_bf16 v[120:123], v[140:143], v[194:197], v[120:123]
	v_mfma_f32_16x16x32_bf16 v[116:119], v[132:135], v[202:205], v[116:119]
	v_mfma_f32_16x16x32_bf16 v[112:115], v[140:143], v[202:205], v[112:115]
	v_mfma_f32_16x16x32_bf16 v[100:103], v[132:135], v[210:213], v[100:103]
	v_mfma_f32_16x16x32_bf16 v[96:99], v[140:143], v[210:213], v[96:99]
	v_mfma_f32_16x16x32_bf16 v[84:87], v[132:135], v[218:221], v[84:87]
	v_mfma_f32_16x16x32_bf16 v[80:83], v[140:143], v[218:221], v[80:83]
	v_mfma_f32_16x16x32_bf16 v[108:111], v[168:171], v[190:193], v[108:111]
	v_mfma_f32_16x16x32_bf16 v[104:107], v[176:179], v[190:193], v[104:107]
	v_mfma_f32_16x16x32_bf16 v[92:95], v[168:171], v[198:201], v[92:95]
	v_mfma_f32_16x16x32_bf16 v[88:91], v[176:179], v[198:201], v[88:91]
	v_mfma_f32_16x16x32_bf16 v[76:79], v[168:171], v[206:209], v[76:79]
	v_mfma_f32_16x16x32_bf16 v[72:75], v[176:179], v[206:209], v[72:75]
	v_mfma_f32_16x16x32_bf16 v[68:71], v[168:171], v[214:217], v[68:71]
	v_mfma_f32_16x16x32_bf16 v[64:67], v[176:179], v[214:217], v[64:67]
	v_mfma_f32_16x16x32_bf16 v[108:111], v[172:175], v[194:197], v[108:111]
	v_mfma_f32_16x16x32_bf16 v[104:107], v[180:183], v[194:197], v[104:107]
	v_mfma_f32_16x16x32_bf16 v[92:95], v[172:175], v[202:205], v[92:95]
	v_mfma_f32_16x16x32_bf16 v[88:91], v[180:183], v[202:205], v[88:91]
	v_mfma_f32_16x16x32_bf16 v[76:79], v[172:175], v[210:213], v[76:79]
	v_mfma_f32_16x16x32_bf16 v[72:75], v[180:183], v[210:213], v[72:75]
	v_mfma_f32_16x16x32_bf16 v[68:71], v[172:175], v[218:221], v[68:71]
	v_mfma_f32_16x16x32_bf16 v[64:67], v[180:183], v[218:221], v[64:67]
	s_setprio 0
	s_barrier
	s_add_i32 m0, s15, 0x10000
	ds_read_b128 v[190:193], v188 offset:16384
	ds_read_b128 v[194:197], v188 offset:17408
	ds_read_b128 v[198:201], v188 offset:18432
	ds_read_b128 v[202:205], v188 offset:19456
	ds_read_b128 v[206:209], v188 offset:20480
	ds_read_b128 v[210:213], v188 offset:21504
	ds_read_b128 v[214:217], v188 offset:22528
	ds_read_b128 v[218:221], v188 offset:23552
	global_load_lds_dwordx4 v148, s[92:93]
	s_add_i32 m0, s15, 0x12000
	s_nop 0
	global_load_lds_dwordx4 v152, s[92:93]
	s_add_i32 m0, s15, 0x14000
	s_add_u32 s92, s92, s21
	s_addc_u32 s93, s93, 0
	global_load_lds_dwordx4 v148, s[92:93]
	s_add_i32 m0, s15, 0x16000
	s_nop 0
	global_load_lds_dwordx4 v152, s[92:93]
	s_mov_b32 m0, s68
	s_nop 0
	global_load_lds_dwordx4 v146, s[42:43]
	s_mov_b32 m0, s23
	s_nop 0
	global_load_lds_dwordx4 v150, s[42:43]
	s_waitcnt vmcnt(8)
	s_waitcnt lgkmcnt(0)
	s_barrier
	s_setprio 1
	s_waitcnt lgkmcnt(0)
	v_mfma_f32_16x16x32_bf16 v[60:63], v[128:131], v[190:193], v[60:63]
	v_mfma_f32_16x16x32_bf16 v[56:59], v[136:139], v[190:193], v[56:59]
	v_mfma_f32_16x16x32_bf16 v[52:55], v[128:131], v[198:201], v[52:55]
	v_mfma_f32_16x16x32_bf16 v[48:51], v[136:139], v[198:201], v[48:51]
	v_mfma_f32_16x16x32_bf16 v[36:39], v[128:131], v[206:209], v[36:39]
	v_mfma_f32_16x16x32_bf16 v[32:35], v[136:139], v[206:209], v[32:35]
	v_mfma_f32_16x16x32_bf16 v[20:23], v[128:131], v[214:217], v[20:23]
	v_mfma_f32_16x16x32_bf16 v[16:19], v[136:139], v[214:217], v[16:19]
	v_mfma_f32_16x16x32_bf16 v[60:63], v[132:135], v[194:197], v[60:63]
	v_mfma_f32_16x16x32_bf16 v[56:59], v[140:143], v[194:197], v[56:59]
	v_mfma_f32_16x16x32_bf16 v[52:55], v[132:135], v[202:205], v[52:55]
	v_mfma_f32_16x16x32_bf16 v[48:51], v[140:143], v[202:205], v[48:51]
	v_mfma_f32_16x16x32_bf16 v[36:39], v[132:135], v[210:213], v[36:39]
	v_mfma_f32_16x16x32_bf16 v[32:35], v[140:143], v[210:213], v[32:35]
	v_mfma_f32_16x16x32_bf16 v[20:23], v[132:135], v[218:221], v[20:23]
	v_mfma_f32_16x16x32_bf16 v[16:19], v[140:143], v[218:221], v[16:19]
	v_mfma_f32_16x16x32_bf16 v[44:47], v[168:171], v[190:193], v[44:47]
	v_mfma_f32_16x16x32_bf16 v[40:43], v[176:179], v[190:193], v[40:43]
	v_mfma_f32_16x16x32_bf16 v[28:31], v[168:171], v[198:201], v[28:31]
	v_mfma_f32_16x16x32_bf16 v[24:27], v[176:179], v[198:201], v[24:27]
	v_mfma_f32_16x16x32_bf16 v[12:15], v[168:171], v[206:209], v[12:15]
	v_mfma_f32_16x16x32_bf16 v[8:11], v[176:179], v[206:209], v[8:11]
	v_mfma_f32_16x16x32_bf16 v[4:7], v[168:171], v[214:217], v[4:7]
	v_mfma_f32_16x16x32_bf16 v[0:3], v[176:179], v[214:217], v[0:3]
	v_mfma_f32_16x16x32_bf16 v[44:47], v[172:175], v[194:197], v[44:47]
	v_mfma_f32_16x16x32_bf16 v[40:43], v[180:183], v[194:197], v[40:43]
	v_mfma_f32_16x16x32_bf16 v[28:31], v[172:175], v[202:205], v[28:31]
	v_mfma_f32_16x16x32_bf16 v[24:27], v[180:183], v[202:205], v[24:27]
	v_mfma_f32_16x16x32_bf16 v[12:15], v[172:175], v[210:213], v[12:15]
	v_mfma_f32_16x16x32_bf16 v[8:11], v[180:183], v[210:213], v[8:11]
	v_mfma_f32_16x16x32_bf16 v[4:7], v[172:175], v[218:221], v[4:7]
	v_mfma_f32_16x16x32_bf16 v[0:3], v[180:183], v[218:221], v[0:3]
	s_setprio 0
	s_barrier
	ds_read_b128 v[128:131], v222 offset:32768
	ds_read_b128 v[132:135], v222 offset:33792
	ds_read_b128 v[136:139], v222 offset:34816
	ds_read_b128 v[140:143], v222 offset:35840
	ds_read_b128 v[168:171], v222 offset:49152
	ds_read_b128 v[172:175], v222 offset:50176
	ds_read_b128 v[176:179], v222 offset:51200
	ds_read_b128 v[180:183], v222 offset:52224
	s_add_u32 s42, s42, s48
	s_addc_u32 s43, s43, 0
	s_mov_b32 m0, s40
	ds_read_b128 v[190:193], v188 offset:32768
	ds_read_b128 v[194:197], v188 offset:33792
	ds_read_b128 v[198:201], v188 offset:34816
	ds_read_b128 v[202:205], v188 offset:35840
	ds_read_b128 v[206:209], v188 offset:36864
	ds_read_b128 v[210:213], v188 offset:37888
	ds_read_b128 v[214:217], v188 offset:38912
	ds_read_b128 v[218:221], v188 offset:39936
	global_load_lds_dwordx4 v146, s[42:43]
	s_mov_b32 m0, s41
	s_nop 0
	global_load_lds_dwordx4 v150, s[42:43]
	s_waitcnt vmcnt(8)
	s_waitcnt lgkmcnt(0)
	s_barrier
	s_setprio 1
	s_waitcnt lgkmcnt(0)
	v_mfma_f32_16x16x32_bf16 v[124:127], v[128:131], v[190:193], v[124:127]
	v_mfma_f32_16x16x32_bf16 v[120:123], v[136:139], v[190:193], v[120:123]
	v_mfma_f32_16x16x32_bf16 v[116:119], v[128:131], v[198:201], v[116:119]
	v_mfma_f32_16x16x32_bf16 v[112:115], v[136:139], v[198:201], v[112:115]
	v_mfma_f32_16x16x32_bf16 v[100:103], v[128:131], v[206:209], v[100:103]
	v_mfma_f32_16x16x32_bf16 v[96:99], v[136:139], v[206:209], v[96:99]
	v_mfma_f32_16x16x32_bf16 v[84:87], v[128:131], v[214:217], v[84:87]
	v_mfma_f32_16x16x32_bf16 v[80:83], v[136:139], v[214:217], v[80:83]
	v_mfma_f32_16x16x32_bf16 v[124:127], v[132:135], v[194:197], v[124:127]
	v_mfma_f32_16x16x32_bf16 v[120:123], v[140:143], v[194:197], v[120:123]
	v_mfma_f32_16x16x32_bf16 v[116:119], v[132:135], v[202:205], v[116:119]
	v_mfma_f32_16x16x32_bf16 v[112:115], v[140:143], v[202:205], v[112:115]
	v_mfma_f32_16x16x32_bf16 v[100:103], v[132:135], v[210:213], v[100:103]
	v_mfma_f32_16x16x32_bf16 v[96:99], v[140:143], v[210:213], v[96:99]
	v_mfma_f32_16x16x32_bf16 v[84:87], v[132:135], v[218:221], v[84:87]
	v_mfma_f32_16x16x32_bf16 v[80:83], v[140:143], v[218:221], v[80:83]
	v_mfma_f32_16x16x32_bf16 v[108:111], v[168:171], v[190:193], v[108:111]
	v_mfma_f32_16x16x32_bf16 v[104:107], v[176:179], v[190:193], v[104:107]
	v_mfma_f32_16x16x32_bf16 v[92:95], v[168:171], v[198:201], v[92:95]
	v_mfma_f32_16x16x32_bf16 v[88:91], v[176:179], v[198:201], v[88:91]
	v_mfma_f32_16x16x32_bf16 v[76:79], v[168:171], v[206:209], v[76:79]
	v_mfma_f32_16x16x32_bf16 v[72:75], v[176:179], v[206:209], v[72:75]
	v_mfma_f32_16x16x32_bf16 v[68:71], v[168:171], v[214:217], v[68:71]
	v_mfma_f32_16x16x32_bf16 v[64:67], v[176:179], v[214:217], v[64:67]
	v_mfma_f32_16x16x32_bf16 v[108:111], v[172:175], v[194:197], v[108:111]
	v_mfma_f32_16x16x32_bf16 v[104:107], v[180:183], v[194:197], v[104:107]
	v_mfma_f32_16x16x32_bf16 v[92:95], v[172:175], v[202:205], v[92:95]
	v_mfma_f32_16x16x32_bf16 v[88:91], v[180:183], v[202:205], v[88:91]
	v_mfma_f32_16x16x32_bf16 v[76:79], v[172:175], v[210:213], v[76:79]
	v_mfma_f32_16x16x32_bf16 v[72:75], v[180:183], v[210:213], v[72:75]
	v_mfma_f32_16x16x32_bf16 v[68:71], v[172:175], v[218:221], v[68:71]
	v_mfma_f32_16x16x32_bf16 v[64:67], v[180:183], v[218:221], v[64:67]
	s_setprio 0
	s_barrier
	s_sub_u32 s92, s92, s21
	s_subb_u32 s93, s93, 0
	s_add_i32 m0, s15, 0x17f80
	ds_read_b128 v[190:193], v188 offset:49152
	ds_read_b128 v[194:197], v188 offset:50176
	ds_read_b128 v[198:201], v188 offset:51200
	ds_read_b128 v[202:205], v188 offset:52224
	ds_read_b128 v[206:209], v188 offset:53248
	ds_read_b128 v[210:213], v188 offset:54272
	ds_read_b128 v[214:217], v188 offset:55296
	ds_read_b128 v[218:221], v188 offset:56320
	global_load_lds_dwordx4 v148, s[92:93] offset:128
	s_add_i32 m0, s15, 0x19f80
	s_nop 0
	global_load_lds_dwordx4 v152, s[92:93] offset:128
	s_add_u32 s92, s92, s21
	s_addc_u32 s93, s93, 0
	s_add_i32 m0, s15, 0x1bf80
	s_add_u32 s6, s6, 0x100
	s_addc_u32 s7, s7, 0
	global_load_lds_dwordx4 v148, s[92:93] offset:128
	s_add_i32 m0, s15, 0x1df80
	s_sub_u32 s42, s42, s48
	s_subb_u32 s43, s43, 0
	global_load_lds_dwordx4 v152, s[92:93] offset:128
	s_add_i32 m0, s64, 0xffffff80
	s_add_u32 s8, s8, 0x100
	s_addc_u32 s66, s66, 0
	global_load_lds_dwordx4 v146, s[42:43] offset:128
	s_add_i32 m0, s65, 0xffffff80
	s_nop 0
	global_load_lds_dwordx4 v150, s[42:43] offset:128
	s_waitcnt vmcnt(8)
	s_waitcnt lgkmcnt(0)
	s_barrier
	s_setprio 1
	s_waitcnt lgkmcnt(0)
	v_mfma_f32_16x16x32_bf16 v[60:63], v[128:131], v[190:193], v[60:63]
	v_mfma_f32_16x16x32_bf16 v[56:59], v[136:139], v[190:193], v[56:59]
	v_mfma_f32_16x16x32_bf16 v[52:55], v[128:131], v[198:201], v[52:55]
	v_mfma_f32_16x16x32_bf16 v[48:51], v[136:139], v[198:201], v[48:51]
	v_mfma_f32_16x16x32_bf16 v[36:39], v[128:131], v[206:209], v[36:39]
	v_mfma_f32_16x16x32_bf16 v[32:35], v[136:139], v[206:209], v[32:35]
	v_mfma_f32_16x16x32_bf16 v[20:23], v[128:131], v[214:217], v[20:23]
	v_mfma_f32_16x16x32_bf16 v[16:19], v[136:139], v[214:217], v[16:19]
	v_mfma_f32_16x16x32_bf16 v[60:63], v[132:135], v[194:197], v[60:63]
	v_mfma_f32_16x16x32_bf16 v[56:59], v[140:143], v[194:197], v[56:59]
	v_mfma_f32_16x16x32_bf16 v[52:55], v[132:135], v[202:205], v[52:55]
	v_mfma_f32_16x16x32_bf16 v[48:51], v[140:143], v[202:205], v[48:51]
	v_mfma_f32_16x16x32_bf16 v[36:39], v[132:135], v[210:213], v[36:39]
	v_mfma_f32_16x16x32_bf16 v[32:35], v[140:143], v[210:213], v[32:35]
	v_mfma_f32_16x16x32_bf16 v[20:23], v[132:135], v[218:221], v[20:23]
	v_mfma_f32_16x16x32_bf16 v[16:19], v[140:143], v[218:221], v[16:19]
	v_mfma_f32_16x16x32_bf16 v[44:47], v[168:171], v[190:193], v[44:47]
	v_mfma_f32_16x16x32_bf16 v[40:43], v[176:179], v[190:193], v[40:43]
	v_mfma_f32_16x16x32_bf16 v[28:31], v[168:171], v[198:201], v[28:31]
	v_mfma_f32_16x16x32_bf16 v[24:27], v[176:179], v[198:201], v[24:27]
	v_mfma_f32_16x16x32_bf16 v[12:15], v[168:171], v[206:209], v[12:15]
	v_mfma_f32_16x16x32_bf16 v[8:11], v[176:179], v[206:209], v[8:11]
	v_mfma_f32_16x16x32_bf16 v[4:7], v[168:171], v[214:217], v[4:7]
	v_mfma_f32_16x16x32_bf16 v[0:3], v[176:179], v[214:217], v[0:3]
	v_mfma_f32_16x16x32_bf16 v[44:47], v[172:175], v[194:197], v[44:47]
	v_mfma_f32_16x16x32_bf16 v[40:43], v[180:183], v[194:197], v[40:43]
	v_mfma_f32_16x16x32_bf16 v[28:31], v[172:175], v[202:205], v[28:31]
	v_mfma_f32_16x16x32_bf16 v[24:27], v[180:183], v[202:205], v[24:27]
	v_mfma_f32_16x16x32_bf16 v[12:15], v[172:175], v[210:213], v[12:15]
	v_mfma_f32_16x16x32_bf16 v[8:11], v[180:183], v[210:213], v[8:11]
	v_mfma_f32_16x16x32_bf16 v[4:7], v[172:175], v[218:221], v[4:7]
	v_mfma_f32_16x16x32_bf16 v[0:3], v[180:183], v[218:221], v[0:3]
	s_setprio 0
	s_barrier
	s_cmp_ge_u32 s90, s55
	s_mov_b32 s42, s90
	s_cbranch_scc0 .LBB0_246
	s_and_b64 vcc, exec, s[86:87]
	s_cbranch_vccz .LBB0_249
	s_barrier
